# + m25: SwiGLU/gate/PLE GEMMs permute their row-tile index so each XCD processes the rows it owns in the per-batch GEMMs; SwiGLU->down and down->gate barriers become XCD-local (no write-back, invalidat
# speedup vs baseline: 1.0076x; 1.0076x over previous
; #define PG8_STAGE(bufoff, gbase, voff) do { _Pragma("unroll") for (int _i = 0; _i < 2; ++_i) \
;         __builtin_amdgcn_global_load_lds((const unsigned*)((const char*)(gbase) + (voff)[_i]), (PG8_LAS unsigned*)(lds + (bufoff) + ldsw + _i * 8192), 16, 0, 0); } while (0)
; #define PG8_BAR __builtin_amdgcn_s_barrier()
;     __host__ __device__ bool next(int i, Unit& u) const {
;         const long L = (long)i * G + c; if (L >= nwg) return false;
;         int wgid = (int)L; { const int q = nwg / NXCD, r = nwg % NXCD, xcd = wgid % NXCD, off = wgid / NXCD; wgid = (xcd < r ? xcd * (q + 1) : r * (q + 1) + (xcd - r) * q) + off; }
;         const int nig = WGM * nN, gid = wgid / nig, fm = gid * WGM, gsz = (nM - fm) < WGM ? (nM - fm) : WGM;
;         u.pm = fm + ((wgid % nig) % gsz); u.pn = (wgid % nig) / gsz; return true;
; template <class Epi, class Sched, bool ALIGN_EPI = false, bool SP2 = false>
; __device__ __forceinline__ void gemm_phase(PG8_LAS unsigned char* lds, const Gemm g, const Sched& S, const Epi& E, const int tid) {
;     ...
;     for (int i = 0; i < 2; ++i) { int R, C; stage_rc(tid * 16 + i * 8192, R, C); const int Rb = Epi::PERM ? ((R & ~31) + perm32(R & 31)) : R;
;         voffA[i] = (unsigned)(R * K + C) * 2u; voffB[i] = (unsigned)(Rb * K + C) * 2u; }
;     const size_t kstep = (size_t)(BK * 2);
;     const size_t hstep = (size_t)HALF * K * 2;
;     const size_t tstep = 2 * hstep;
;     const unsigned ldsw = (unsigned)wid * 1024u;
;     const int aoff = lds_byte(wr * 64 + fr, fq * 8), boff = lds_byte(wc * 32 + fr, fq * 8);
;     ...
;     Unit cur, nxt; int ui = 0;
;     if (!S.next(0, cur)) return;
;     f32x4 acc[2][2][4][2];
; #pragma unroll
;     for (int a = 0; a < 2; ++a)
; #pragma unroll
;         for (int b = 0; b < 2; ++b)
; #pragma unroll
;             for (int m = 0; m < 4; ++m)
; #pragma unroll
;                 for (int n = 0; n < 2; ++n) acc[a][b][m][n] = (f32x4){0.f, 0.f, 0.f, 0.f};
;     bf16x8 At[4][2], B0[2][2], B1[2][2];
;     const char* cA = (const char*)g.A + (size_t)cur.pm * tstep; const char* cB = (const char*)g.Bt + (size_t)cur.pn * tstep;
;     S.a_ready(cur);
;     if constexpr (SP2) {
;         PG8_STAGE(PG8_SB(0, 0), cB, voffB); PG8_STAGE(PG8_SB(0, 1), cB + hstep, voffB); PG8_STAGE(PG8_SA(0, 0), cA, voffA); PG8_STAGE(PG8_SA(0, 1), cA + hstep, voffA);
;         if (wr == 1) PG8_BAR;
.LBB0_25:
	v_ashrrev_i32_e32 v1, 31, v210
	v_lshrrev_b32_e32 v1, 26, v1
	v_add_u32_e32 v1, v210, v1
	v_ashrrev_i32_e32 v8, 6, v1
	v_bfe_i32 v1, v210, 27, 1
	v_lshlrev_b32_e32 v0, 4, v210
	v_lshrrev_b32_e32 v1, 22, v1
	v_add_u32_e32 v1, v0, v1
	v_and_b32_e32 v1, 0xfffffc00, v1
	v_sub_u32_e32 v1, v0, v1
	v_lshrrev_b32_e32 v2, 4, v1
	v_bitop3_b32 v1, v2, v1, 32 bitop3:0x6c
	v_ashrrev_i32_e32 v3, 31, v1
	v_lshrrev_b32_e32 v3, 26, v3
	v_add_u32_e32 v3, v1, v3
	v_lshlrev_b32_e32 v2, 3, v8
	v_ashrrev_i32_e32 v9, 6, v3
	v_and_b32_e32 v3, 0xc0, v3
	v_and_b32_e32 v2, -16, v2
	v_sub_u32_e32 v1, v1, v3
	v_mov_b32_e32 v6, 1
	v_add_u32_e32 v2, v9, v2
	v_ashrrev_i16_sdwa v1, v6, sext(v1) dst_sel:DWORD dst_unused:UNUSED_PAD src0_sel:DWORD src1_sel:BYTE_0
	v_lshlrev_b32_e32 v4, 5, v8
	v_bfe_i32 v10, v1, 0, 16
	v_lshlrev_b32_e32 v1, 1, v2
	v_lshrrev_b32_e32 v3, 2, v2
	v_and_b32_e32 v5, 3, v9
	s_mov_b32 s9, 0x1fffe0
	v_and_b32_e32 v4, 32, v4
	v_and_b32_e32 v1, 24, v1
	v_and_b32_e32 v3, 4, v3
	v_and_or_b32 v5, v2, s9, v5
	v_or3_b32 v1, v5, v3, v1
	v_add_lshl_u32 v3, v4, v10, 1
	v_add_u32_e32 v0, 0x2000, v0
	v_lshl_add_u32 v192, v1, 11, v3
	v_ashrrev_i32_e32 v1, 31, v0
	v_lshrrev_b32_e32 v1, 22, v1
	v_add_u32_e32 v1, v0, v1
	v_ashrrev_i32_e32 v11, 10, v1
	v_mul_i32_i24_e32 v1, 0x400, v11
	v_sub_u32_e32 v0, v0, v1
	s_add_u32 s1, s30, 0x13a00000
	v_lshrrev_b32_e32 v1, 4, v0
	s_addc_u32 s2, s31, 0
	v_bitop3_b32 v0, v1, v0, 32 bitop3:0x6c
	s_add_u32 s26, s30, 0x2780000
	s_waitcnt vmcnt(0)
	v_lshl_add_u32 v128, v2, 11, v3
	v_ashrrev_i32_e32 v2, 31, v0
	s_addc_u32 s34, s31, 0
	v_lshrrev_b32_e32 v2, 26, v2
	s_add_i32 s6, s8, s6
	v_lshlrev_b32_e32 v1, 3, v11
	v_add_u32_e32 v2, v0, v2
	s_ashr_i32 s8, s6, 31
	v_and_b32_e32 v1, -16, v1
	v_ashrrev_i32_e32 v12, 6, v2
	s_lshr_b32 s8, s8, 28
	v_add_u32_e32 v1, v12, v1
	v_and_b32_e32 v4, 3, v12
	s_add_i32 s8, s6, s8
	v_and_or_b32 v4, v1, s9, v4
	s_ashr_i32 s9, s8, 4
	s_and_b32 s8, s8, 0xfff0
	s_sub_i32 s8, s6, s8
	s_bfe_i32 s6, s8, 0x80000
	s_bfe_u32 s6, s6, 0x2000d
	s_add_i32 s14, s8, s6
	s_bfe_i32 s6, s14, 0x80000
	s_and_b32 s14, s14, 0xfc
	s_sub_i32 s8, s8, s14
	s_lshl_b32 s9, s9, 2
	s_sext_i32_i16 s6, s6
	s_sext_i32_i8 s8, s8
	s_ashr_i32 s7, s10, 8
	s_lshr_b32 s6, s6, 2
	s_add_i32 s22, s9, s8
	s_lshr_b32 s98, s22, 3
	s_and_b32 s98, s98, 1
	s_lshl_b32 s98, s98, 6
	s_and_b32 s99, s22, 7
	s_add_i32 s98, s98, s99
	s_lshr_b32 s22, s22, 4
	s_lshl_b32 s22, s22, 3
	s_add_i32 s22, s22, s98
	v_and_b32_e32 v2, 0xc0, v2
	s_ashr_i32 s11, s10, 6
	s_ashr_i32 s23, s22, 31
	s_bfe_i64 s[14:15], s[6:7], 0x100000
	v_sub_u32_e32 v0, v0, v2
	s_lshl_b32 s35, s11, 10
	s_lshl_b64 s[8:9], s[22:23], 19
	s_lshl_b64 s[14:15], s[14:15], 19
	v_ashrrev_i16_sdwa v0, v6, sext(v0) dst_sel:DWORD dst_unused:UNUSED_PAD src0_sel:DWORD src1_sel:BYTE_0
	s_add_u32 s58, s26, s14
	v_lshlrev_b32_e32 v3, 5, v11
	v_bfe_i32 v13, v0, 0, 16
	v_lshlrev_b32_e32 v0, 1, v1
	v_lshrrev_b32_e32 v2, 2, v1
	s_addc_u32 s59, s34, s15
	s_add_i32 s38, s35, 0
	v_and_b32_e32 v3, 32, v3
	v_and_b32_e32 v0, 24, v0
	v_and_b32_e32 v2, 4, v2
	s_add_i32 m0, s38, 0x10000
	v_or3_b32 v0, v4, v2, v0
	v_add_lshl_u32 v2, v3, v13, 1
	global_load_lds_dwordx4 v192, s[58:59]
	s_add_i32 m0, s38, 0x12000
	v_lshl_add_u32 v132, v0, 11, v2
	s_add_u32 s14, s58, 0x40000
	global_load_lds_dwordx4 v132, s[58:59]
	s_addc_u32 s15, s59, 0
	s_add_i32 m0, s38, 0x14000
	v_lshl_add_u32 v130, v1, 11, v2
	global_load_lds_dwordx4 v192, s[14:15]
	s_add_i32 m0, s38, 0x16000
	s_add_u32 s44, s1, s8
	s_addc_u32 s45, s2, s9
	s_add_i32 s40, s38, 0x2000
	global_load_lds_dwordx4 v132, s[14:15]
	s_mov_b32 m0, s38
	s_add_u32 s8, s44, 0x40000
	global_load_lds_dwordx4 v128, s[44:45]
	s_mov_b32 m0, s40
	s_addc_u32 s9, s45, 0
	s_add_i32 s41, s38, 0x4000
	global_load_lds_dwordx4 v130, s[44:45]
	s_mov_b32 m0, s41
	s_add_i32 s46, s38, 0x6000
	global_load_lds_dwordx4 v128, s[8:9]
	s_mov_b32 m0, s46
	v_mov_b32_e32 v133, v193
	global_load_lds_dwordx4 v130, s[8:9]
	v_mov_b32_e32 v129, v193
	v_mov_b32_e32 v131, v193
	s_cmp_eq_u32 s7, 1
	v_lshl_add_u64 v[6:7], s[58:59], 0, v[192:193]
	v_lshl_add_u64 v[4:5], s[58:59], 0, v[132:133]
	v_lshl_add_u64 v[0:1], s[44:45], 0, v[128:129]
	s_cselect_b64 s[8:9], -1, 0
	s_cmp_lg_u32 s7, 1
	v_lshl_add_u64 v[2:3], s[44:45], 0, v[130:131]
	s_cbranch_scc1 .LBB0_27
	s_barrier

;     __host__ __device__ bool next(int i, Unit& u) const {
;         const long L = (long)i * G + c; if (L >= nwg) return false;
;         int wgid = (int)L; { const int q = nwg / NXCD, r = nwg % NXCD, xcd = wgid % NXCD, off = wgid / NXCD; wgid = (xcd < r ? xcd * (q + 1) : r * (q + 1) + (xcd - r) * q) + off; }
;         const int nig = WGM * nN, gid = wgid / nig, fm = gid * WGM, gsz = (nM - fm) < WGM ? (nM - fm) : WGM;
;         u.pm = fm + ((wgid % nig) % gsz); u.pn = (wgid % nig) / gsz; return true;
.LBB0_36:
	s_ashr_i32 s14, s16, 3
	s_add_i32 s14, s18, s14
	s_ashr_i32 s15, s14, 31
	s_lshr_b32 s15, s15, 28
	s_add_i32 s15, s14, s15
	s_ashr_i32 s16, s15, 4
	s_lshl_b32 s16, s16, 2
	s_sub_i32 s17, 0x80, s16
	s_min_i32 s17, s17, 4
	s_abs_i32 s18, s17
	v_cvt_f32_u32_e32 v0, s18
	s_sub_i32 s20, 0, s18
	s_and_b32 s15, s15, -16
	s_sub_i32 s15, s14, s15
	v_rcp_iflag_f32_e32 v0, v0
	s_abs_i32 s14, s15
	s_xor_b32 s19, s15, s17
	s_ashr_i32 s19, s19, 31
	v_mul_f32_e32 v0, 0x4f7ffffe, v0
	v_cvt_u32_f32_e32 v0, v0
	s_nop 0
	v_readfirstlane_b32 s21, v0
	s_mul_i32 s20, s20, s21
	s_mul_hi_u32 s20, s21, s20
	s_add_i32 s21, s21, s20
	s_mul_hi_u32 s20, s14, s21
	s_mul_i32 s21, s20, s18
	s_sub_i32 s14, s14, s21
	s_add_i32 s60, s20, 1
	s_sub_i32 s21, s14, s18
	s_cmp_ge_u32 s14, s18
	s_cselect_b32 s20, s60, s20
	s_cselect_b32 s14, s21, s14
	s_add_i32 s21, s20, 1
	s_cmp_ge_u32 s14, s18
	s_cselect_b32 s14, s21, s20
	s_xor_b32 s14, s14, s19
	s_sub_i32 s14, s14, s19
	s_mul_i32 s17, s14, s17
	s_sub_i32 s15, s15, s17
	s_add_i32 s16, s16, s15
	s_lshr_b32 s98, s16, 3
	s_and_b32 s98, s98, 1
	s_lshl_b32 s98, s98, 6
	s_and_b32 s99, s16, 7
	s_add_i32 s98, s98, s99
	s_lshr_b32 s16, s16, 4
	s_lshl_b32 s16, s16, 3
	s_add_i32 s16, s16, s98

; #define PG8_STAGE(bufoff, gbase, voff) do { _Pragma("unroll") for (int _i = 0; _i < 2; ++_i) \
;         __builtin_amdgcn_global_load_lds((const unsigned*)((const char*)(gbase) + (voff)[_i]), (PG8_LAS unsigned*)(lds + (bufoff) + ldsw + _i * 8192), 16, 0, 0); } while (0)
; #define PG8_BAR __builtin_amdgcn_s_barrier()
;     __host__ __device__ bool next(int i, Unit& u) const {
;         const long L = (long)i * G + c; if (L >= nwg) return false;
;         int wgid = (int)L; { const int q = nwg / NXCD, r = nwg % NXCD, xcd = wgid % NXCD, off = wgid / NXCD; wgid = (xcd < r ? xcd * (q + 1) : r * (q + 1) + (xcd - r) * q) + off; }
;         const int nig = WGM * nN, gid = wgid / nig, fm = gid * WGM, gsz = (nM - fm) < WGM ? (nM - fm) : WGM;
;         u.pm = fm + ((wgid % nig) % gsz); u.pn = (wgid % nig) / gsz; return true;
; template <class Epi, class Sched, bool ALIGN_EPI = false, bool SP2 = false>
; __device__ __forceinline__ void gemm_phase(PG8_LAS unsigned char* lds, const Gemm g, const Sched& S, const Epi& E, const int tid) {
;     ...
;     for (int i = 0; i < 2; ++i) { int R, C; stage_rc(tid * 16 + i * 8192, R, C); const int Rb = Epi::PERM ? ((R & ~31) + perm32(R & 31)) : R;
;         voffA[i] = (unsigned)(R * K + C) * 2u; voffB[i] = (unsigned)(Rb * K + C) * 2u; }
;     const size_t kstep = (size_t)(BK * 2);
;     const size_t hstep = (size_t)HALF * K * 2;
;     const size_t tstep = 2 * hstep;
;     const unsigned ldsw = (unsigned)wid * 1024u;
;     const int aoff = lds_byte(wr * 64 + fr, fq * 8), boff = lds_byte(wc * 32 + fr, fq * 8);
;     ...
;     Unit cur, nxt; int ui = 0;
;     if (!S.next(0, cur)) return;
;     f32x4 acc[2][2][4][2];
; #pragma unroll
;     for (int a = 0; a < 2; ++a)
; #pragma unroll
;         for (int b = 0; b < 2; ++b)
; #pragma unroll
;             for (int m = 0; m < 4; ++m)
; #pragma unroll
;                 for (int n = 0; n < 2; ++n) acc[a][b][m][n] = (f32x4){0.f, 0.f, 0.f, 0.f};
;     bf16x8 At[4][2], B0[2][2], B1[2][2];
;     const char* cA = (const char*)g.A + (size_t)cur.pm * tstep; const char* cB = (const char*)g.Bt + (size_t)cur.pn * tstep;
;     S.a_ready(cur);
;     if constexpr (SP2) {
;         PG8_STAGE(PG8_SB(0, 0), cB, voffB); PG8_STAGE(PG8_SB(0, 1), cB + hstep, voffB); PG8_STAGE(PG8_SA(0, 0), cA, voffA); PG8_STAGE(PG8_SA(0, 1), cA + hstep, voffA);
;         if (wr == 1) PG8_BAR;
.LBB0_50:
	v_bfe_i32 v3, v0, 27, 1
	v_lshlrev_b32_e32 v1, 4, v0
	v_lshrrev_b32_e32 v3, 22, v3
	v_add_u32_e32 v3, v1, v3
	v_and_b32_e32 v3, 0xfffffc00, v3
	v_sub_u32_e32 v3, v1, v3
	v_ashrrev_i32_e32 v2, 31, v0
	v_lshrrev_b32_e32 v4, 4, v3
	v_lshrrev_b32_e32 v2, 26, v2
	v_bitop3_b32 v3, v4, v3, 32 bitop3:0x6c
	v_add_u32_e32 v2, v0, v2
	v_ashrrev_i32_e32 v5, 31, v3
	v_ashrrev_i32_e32 v2, 6, v2
	v_lshrrev_b32_e32 v5, 26, v5
	v_lshlrev_b32_e32 v4, 3, v2
	v_add_u32_e32 v5, v3, v5
	v_and_b32_e32 v4, -16, v4
	v_ashrrev_i32_e32 v6, 6, v5
	v_and_b32_e32 v5, 0xc0, v5
	v_add_u32_e32 v4, v6, v4
	v_sub_u32_e32 v3, v3, v5
	v_mov_b32_e32 v8, 1
	v_lshlrev_b32_e32 v2, 5, v2
	v_ashrrev_i16_sdwa v3, v8, sext(v3) dst_sel:DWORD dst_unused:UNUSED_PAD src0_sel:DWORD src1_sel:BYTE_0
	v_lshlrev_b32_e32 v5, 1, v4
	v_lshrrev_b32_e32 v7, 2, v4
	v_and_b32_e32 v6, 3, v6
	s_mov_b32 s11, 0x7fffe0
	v_and_b32_e32 v2, 32, v2
	v_bfe_i32 v3, v3, 0, 16
	v_and_b32_e32 v5, 24, v5
	v_and_b32_e32 v7, 4, v7
	v_and_or_b32 v6, v4, s11, v6
	v_or3_b32 v5, v6, v7, v5
	v_add_lshl_u32 v2, v2, v3, 1
	v_add_u32_e32 v1, 0x2000, v1
	s_waitcnt vmcnt(0)
	v_lshl_add_u32 v128, v4, 9, v2
	v_lshl_add_u32 v192, v5, 9, v2
	v_ashrrev_i32_e32 v2, 31, v1
	v_lshrrev_b32_e32 v2, 22, v2
	v_add_u32_e32 v2, v1, v2
	v_ashrrev_i32_e32 v2, 10, v2
	v_readlane_b32 s0, v255, 18
	v_mul_i32_i24_e32 v3, 0x400, v2
	v_readlane_b32 s1, v255, 19
	v_sub_u32_e32 v1, v1, v3
	s_and_b64 s[0:1], s[0:1], exec
	v_lshrrev_b32_e32 v3, 4, v1
	s_mov_b32 s0, 0x1da00000
	v_bitop3_b32 v1, v3, v1, 32 bitop3:0x6c
	s_cselect_b32 s0, s0, 0x17a00000
	v_ashrrev_i32_e32 v4, 31, v1
	s_waitcnt lgkmcnt(0)
	s_add_u32 s0, s8, s0
	v_lshrrev_b32_e32 v4, 26, v4
	s_addc_u32 s1, s9, 0
	v_lshlrev_b32_e32 v3, 3, v2
	v_add_u32_e32 v4, v1, v4
	s_add_u32 s2, s8, 0x2980000
	v_and_b32_e32 v3, -16, v3
	v_ashrrev_i32_e32 v5, 6, v4
	s_addc_u32 s26, s9, 0
	v_add_u32_e32 v3, v5, v3
	v_and_b32_e32 v5, 3, v5
	s_add_i32 s10, s14, s10
	v_and_or_b32 v5, v3, s11, v5
	s_ashr_i32 s11, s10, 31
	s_lshr_b32 s11, s11, 28
	s_add_i32 s11, s10, s11
	s_ashr_i32 s14, s11, 4
	s_and_b32 s11, s11, 0xfff0
	s_sub_i32 s10, s10, s11
	s_bfe_i32 s11, s10, 0x80000
	s_bfe_u32 s11, s11, 0x2000d
	s_add_i32 s11, s10, s11
	s_bfe_i32 s15, s11, 0x80000
	s_and_b32 s11, s11, 0xfc
	s_sub_i32 s10, s10, s11
	s_lshl_b32 s14, s14, 2
	s_sext_i32_i16 s15, s15
	s_sext_i32_i8 s10, s10
	s_lshr_b32 s16, s15, 2
	s_add_i32 s78, s14, s10
	s_lshr_b32 s98, s78, 3
	s_and_b32 s98, s98, 1
	s_lshl_b32 s98, s98, 6
	s_and_b32 s99, s78, 7
	s_add_i32 s98, s98, s99
	s_lshr_b32 s78, s78, 4
	s_lshl_b32 s78, s78, 3
	s_add_i32 s78, s78, s98
	s_ashr_i32 s21, s17, 6
	s_ashr_i32 s79, s78, 31
	s_bfe_i64 s[14:15], s[16:17], 0x100000
	s_ashr_i32 s20, s17, 8
	v_and_b32_e32 v4, 0xc0, v4
	s_lshl_b32 s34, s21, 10
	s_lshl_b64 s[10:11], s[78:79], 17
	s_lshl_b64 s[14:15], s[14:15], 17
	v_sub_u32_e32 v1, v1, v4
	s_add_u32 s82, s2, s14
	v_lshlrev_b32_e32 v2, 5, v2
	v_ashrrev_i16_sdwa v1, v8, sext(v1) dst_sel:DWORD dst_unused:UNUSED_PAD src0_sel:DWORD src1_sel:BYTE_0
	v_lshlrev_b32_e32 v4, 1, v3
	v_lshrrev_b32_e32 v6, 2, v3
	s_addc_u32 s83, s26, s15
	s_add_i32 s35, s34, 0
	v_and_b32_e32 v2, 32, v2
	v_bfe_i32 v1, v1, 0, 16
	v_and_b32_e32 v4, 24, v4
	v_and_b32_e32 v6, 4, v6
	s_add_i32 m0, s35, 0x10000
	v_or3_b32 v4, v5, v6, v4
	v_add_lshl_u32 v1, v2, v1, 1
	global_load_lds_dwordx4 v192, s[82:83]
	s_add_i32 m0, s35, 0x12000
	v_lshl_add_u32 v132, v4, 9, v1
	s_add_u32 s14, s82, 0x10000
	global_load_lds_dwordx4 v132, s[82:83]
	s_addc_u32 s15, s83, 0
	s_add_i32 m0, s35, 0x14000
	v_lshl_add_u32 v130, v3, 9, v1
	global_load_lds_dwordx4 v192, s[14:15]
	s_add_i32 m0, s35, 0x16000
	s_add_u32 s80, s0, s10
	s_addc_u32 s81, s1, s11
	s_add_i32 s38, s35, 0x2000
	global_load_lds_dwordx4 v132, s[14:15]
	s_mov_b32 m0, s35
	s_add_u32 s10, s80, 0x10000
	global_load_lds_dwordx4 v128, s[80:81]
	s_mov_b32 m0, s38
	s_addc_u32 s11, s81, 0
	s_add_i32 s40, s35, 0x4000
	global_load_lds_dwordx4 v130, s[80:81]
	s_mov_b32 m0, s40
	s_add_i32 s41, s35, 0x6000
	global_load_lds_dwordx4 v128, s[10:11]
	s_mov_b32 m0, s41
	s_cmp_eq_u32 s20, 1
	global_load_lds_dwordx4 v130, s[10:11]
	s_load_dwordx2 s[10:11], s[6:7], 0xb0
	s_cselect_b64 s[14:15], -1, 0
	s_cmp_lg_u32 s20, 1
	s_cbranch_scc1 .LBB0_52
	s_barrier

;     __host__ __device__ bool next(int i, Unit& u) const {
;         const long L = (long)i * G + c; if (L >= nwg) return false;
;         int wgid = (int)L; { const int q = nwg / NXCD, r = nwg % NXCD, xcd = wgid % NXCD, off = wgid / NXCD; wgid = (xcd < r ? xcd * (q + 1) : r * (q + 1) + (xcd - r) * q) + off; }
;         const int nig = WGM * nN, gid = wgid / nig, fm = gid * WGM, gsz = (nM - fm) < WGM ? (nM - fm) : WGM;
;         u.pm = fm + ((wgid % nig) % gsz); u.pn = (wgid % nig) / gsz; return true;
.LBB0_60:
	s_ashr_i32 s20, s22, 3
	s_add_i32 s20, s44, s20
	s_ashr_i32 s21, s20, 31
	s_lshr_b32 s21, s21, 28
	s_add_i32 s21, s20, s21
	s_ashr_i32 s22, s21, 4
	s_lshl_b32 s22, s22, 2
	s_sub_i32 s23, 0x80, s22
	s_min_i32 s23, s23, 4
	s_abs_i32 s44, s23
	v_cvt_f32_u32_e32 v0, s44
	s_sub_i32 s55, 0, s44
	s_and_b32 s21, s21, -16
	s_sub_i32 s21, s20, s21
	v_rcp_iflag_f32_e32 v0, v0
	s_abs_i32 s20, s21
	s_xor_b32 s45, s21, s23
	s_ashr_i32 s45, s45, 31
	v_mul_f32_e32 v0, 0x4f7ffffe, v0
	v_cvt_u32_f32_e32 v0, v0
	s_nop 0
	v_readfirstlane_b32 s58, v0
	s_mul_i32 s55, s55, s58
	s_mul_hi_u32 s55, s58, s55
	s_add_i32 s58, s58, s55
	s_mul_hi_u32 s55, s20, s58
	s_mul_i32 s58, s55, s44
	s_sub_i32 s20, s20, s58
	s_add_i32 s59, s55, 1
	s_sub_i32 s58, s20, s44
	s_cmp_ge_u32 s20, s44
	s_cselect_b32 s55, s59, s55
	s_cselect_b32 s20, s58, s20
	s_add_i32 s58, s55, 1
	s_cmp_ge_u32 s20, s44
	s_cselect_b32 s20, s58, s55
	s_xor_b32 s20, s20, s45
	s_sub_i32 s20, s20, s45
	s_mul_i32 s23, s20, s23
	s_sub_i32 s21, s21, s23
	s_add_i32 s22, s22, s21
	s_lshr_b32 s98, s22, 3
	s_and_b32 s98, s98, 1
	s_lshl_b32 s98, s98, 6
	s_and_b32 s99, s22, 7
	s_add_i32 s98, s98, s99
	s_lshr_b32 s22, s22, 4
	s_lshl_b32 s22, s22, 3
	s_add_i32 s22, s22, s98

; #define PG8_STAGE(bufoff, gbase, voff) do { _Pragma("unroll") for (int _i = 0; _i < 2; ++_i) \
;         __builtin_amdgcn_global_load_lds((const unsigned*)((const char*)(gbase) + (voff)[_i]), (PG8_LAS unsigned*)(lds + (bufoff) + ldsw + _i * 8192), 16, 0, 0); } while (0)
; #define PG8_BAR __builtin_amdgcn_s_barrier()
;     __host__ __device__ bool next(int i, Unit& u) const {
;         const long L = (long)i * G + c; if (L >= nwg) return false;
;         int wgid = (int)L; { const int q = nwg / NXCD, r = nwg % NXCD, xcd = wgid % NXCD, off = wgid / NXCD; wgid = (xcd < r ? xcd * (q + 1) : r * (q + 1) + (xcd - r) * q) + off; }
;         const int nig = WGM * nN, gid = wgid / nig, fm = gid * WGM, gsz = (nM - fm) < WGM ? (nM - fm) : WGM;
;         u.pm = fm + ((wgid % nig) % gsz); u.pn = (wgid % nig) / gsz; return true;
; template <class Epi, class Sched, bool ALIGN_EPI = false, bool SP2 = false>
; __device__ __forceinline__ void gemm_phase(PG8_LAS unsigned char* lds, const Gemm g, const Sched& S, const Epi& E, const int tid) {
;     ...
;     for (int i = 0; i < 2; ++i) { int R, C; stage_rc(tid * 16 + i * 8192, R, C); const int Rb = Epi::PERM ? ((R & ~31) + perm32(R & 31)) : R;
;         voffA[i] = (unsigned)(R * K + C) * 2u; voffB[i] = (unsigned)(Rb * K + C) * 2u; }
;     const size_t kstep = (size_t)(BK * 2);
;     const size_t hstep = (size_t)HALF * K * 2;
;     const size_t tstep = 2 * hstep;
;     const unsigned ldsw = (unsigned)wid * 1024u;
;     const int aoff = lds_byte(wr * 64 + fr, fq * 8), boff = lds_byte(wc * 32 + fr, fq * 8);
;     ...
;     Unit cur, nxt; int ui = 0;
;     if (!S.next(0, cur)) return;
;     f32x4 acc[2][2][4][2];
; #pragma unroll
;     for (int a = 0; a < 2; ++a)
; #pragma unroll
;         for (int b = 0; b < 2; ++b)
; #pragma unroll
;             for (int m = 0; m < 4; ++m)
; #pragma unroll
;                 for (int n = 0; n < 2; ++n) acc[a][b][m][n] = (f32x4){0.f, 0.f, 0.f, 0.f};
;     bf16x8 At[4][2], B0[2][2], B1[2][2];
;     const char* cA = (const char*)g.A + (size_t)cur.pm * tstep; const char* cB = (const char*)g.Bt + (size_t)cur.pn * tstep;
;     S.a_ready(cur);
;     if constexpr (SP2) {
;         PG8_STAGE(PG8_SB(0, 0), cB, voffB); PG8_STAGE(PG8_SB(0, 1), cB + hstep, voffB); PG8_STAGE(PG8_SA(0, 0), cA, voffA); PG8_STAGE(PG8_SA(0, 1), cA + hstep, voffA);
;         if (wr == 1) PG8_BAR;
.LBB0_134:
	s_cmpk_gt_i32 s68, 0xaff
	v_readfirstlane_b32 s7, v210
	s_cbranch_scc1 .LBB0_150
	v_lshlrev_b32_e32 v0, 4, v210
	v_add_u32_e32 v1, 0x2000, v0
	v_ashrrev_i32_e32 v2, 31, v1
	v_lshrrev_b32_e32 v2, 22, v2
	v_add_u32_e32 v2, v1, v2
	v_ashrrev_i32_e32 v8, 10, v2
	v_mul_i32_i24_e32 v2, 0x400, v8
	v_sub_u32_e32 v1, v1, v2
	v_lshrrev_b32_e32 v2, 4, v1
	v_bitop3_b32 v1, v2, v1, 32 bitop3:0x6c
	v_ashrrev_i32_e32 v2, 31, v1
	v_lshrrev_b32_e32 v2, 26, v2
	v_add_u32_e32 v2, v1, v2
	v_lshlrev_b32_e32 v3, 3, v8
	v_ashrrev_i32_e32 v9, 6, v2
	v_and_b32_e32 v3, -16, v3
	v_add_u32_e32 v3, v9, v3
	v_and_b32_e32 v4, 3, v9
	s_mov_b32 s6, 0x1fffe0
	v_lshrrev_b32_e32 v5, 2, v3
	v_lshlrev_b32_e32 v6, 1, v3
	v_and_or_b32 v4, v3, s6, v4
	v_and_b32_e32 v5, 4, v5
	v_and_b32_e32 v6, 24, v6
	v_and_b32_e32 v2, 0xc0, v2
	v_or3_b32 v4, v4, v5, v6
	v_sub_u32_e32 v1, v1, v2
	v_mov_b32_e32 v6, 1
	v_lshlrev_b32_e32 v5, 5, v8
	v_ashrrev_i16_sdwa v1, v6, sext(v1) dst_sel:DWORD dst_unused:UNUSED_PAD src0_sel:DWORD src1_sel:BYTE_0
	v_and_b32_e32 v5, 32, v5
	v_bfe_i32 v10, v1, 0, 16
	v_add_lshl_u32 v1, v5, v10, 1
	s_waitcnt vmcnt(0)
	v_lshl_add_u32 v128, v4, 11, v1
	v_lshl_add_u32 v130, v3, 11, v1
	v_bfe_i32 v1, v210, 27, 1
	v_lshrrev_b32_e32 v1, 22, v1
	v_add_u32_e32 v1, v0, v1
	v_and_b32_e32 v1, 0xfffffc00, v1
	v_readlane_b32 s0, v255, 18
	v_sub_u32_e32 v0, v0, v1
	v_readlane_b32 s1, v255, 19
	v_lshrrev_b32_e32 v1, 4, v0
	v_ashrrev_i32_e32 v2, 31, v210
	s_and_b64 s[0:1], s[0:1], exec
	v_bitop3_b32 v0, v1, v0, 32 bitop3:0x6c
	v_lshrrev_b32_e32 v2, 26, v2
	s_cselect_b32 s0, 0x4a00000, s25
	v_ashrrev_i32_e32 v1, 31, v0
	v_add_u32_e32 v2, v210, v2
	s_add_u32 s0, s30, s0
	v_lshrrev_b32_e32 v1, 26, v1
	v_ashrrev_i32_e32 v12, 6, v2
	s_addc_u32 s1, s31, 0
	v_add_u32_e32 v1, v0, v1
	v_lshlrev_b32_e32 v2, 3, v12
	s_add_u32 s2, s30, 0x1700000
	v_ashrrev_i32_e32 v11, 6, v1
	v_and_b32_e32 v2, -16, v2
	s_addc_u32 s26, s31, 0
	v_add_u32_e32 v2, v11, v2
	v_and_b32_e32 v3, 3, v11
	s_ashr_i32 s35, s68, 31
	v_and_or_b32 v3, v2, s6, v3
	s_lshr_b32 s6, s35, 29
	s_add_i32 s6, s68, s6
	s_ashr_i32 s10, s7, 6
	s_ashr_i32 s8, s6, 3
	s_and_b32 s6, s6, -8
	s_ashr_i32 s11, s7, 8
	s_lshl_b32 s34, s10, 10
	s_sub_i32 s6, s68, s6
	s_cmp_lt_i32 s6, 0
	s_movk_i32 s9, 0x161
	s_cselect_b32 s9, s9, 0x160
	s_mul_i32 s6, s9, s6
	s_add_i32 s6, s6, s8
	s_mul_hi_i32 s8, s6, 0x2e8ba2e9
	s_lshr_b32 s9, s8, 31
	s_ashr_i32 s8, s8, 4
	s_add_i32 s8, s8, s9
	s_lshl_b32 s9, s8, 2
	s_mulk_i32 s8, 0x58
	s_sub_i32 s8, s6, s8
	s_bfe_i32 s6, s8, 0x80000
	s_bfe_u32 s6, s6, 0x2000d
	s_add_i32 s14, s8, s6
	s_bfe_i32 s6, s14, 0x80000
	s_and_b32 s14, s14, 0xfc
	s_sub_i32 s8, s8, s14
	s_sext_i32_i16 s6, s6
	s_sext_i32_i8 s8, s8
	v_lshrrev_b32_e32 v4, 2, v2
	v_lshlrev_b32_e32 v5, 1, v2
	v_and_b32_e32 v1, 0xc0, v1
	s_lshr_b32 s6, s6, 2
	s_add_i32 s22, s9, s8
	s_lshr_b32 s98, s22, 3
	s_and_b32 s98, s98, 1
	s_lshl_b32 s98, s98, 6
	s_and_b32 s99, s22, 7
	s_add_i32 s98, s98, s99
	s_lshr_b32 s22, s22, 4
	s_lshl_b32 s22, s22, 3
	s_add_i32 s22, s22, s98
	v_and_b32_e32 v4, 4, v4
	v_and_b32_e32 v5, 24, v5
	v_sub_u32_e32 v0, v0, v1
	s_ashr_i32 s23, s22, 31
	s_bfe_i64 s[14:15], s[6:7], 0x100000
	v_or3_b32 v3, v3, v4, v5
	v_lshlrev_b32_e32 v4, 5, v12
	v_ashrrev_i16_sdwa v0, v6, sext(v0) dst_sel:DWORD dst_unused:UNUSED_PAD src0_sel:DWORD src1_sel:BYTE_0
	s_lshl_b64 s[8:9], s[22:23], 19
	s_lshl_b64 s[14:15], s[14:15], 19
	v_and_b32_e32 v4, 32, v4
	v_bfe_i32 v13, v0, 0, 16
	s_add_u32 s58, s2, s14
	v_add_lshl_u32 v0, v4, v13, 1
	s_addc_u32 s59, s26, s15
	s_add_i32 s38, s34, 0
	v_lshl_add_u32 v192, v3, 11, v0
	s_add_i32 m0, s38, 0x10000
	v_lshl_add_u32 v132, v2, 11, v0
	global_load_lds_dwordx4 v192, s[58:59]
	s_add_i32 m0, s38, 0x12000
	s_add_u32 s14, s58, 0x40000
	global_load_lds_dwordx4 v128, s[58:59]
	s_addc_u32 s15, s59, 0
	s_add_i32 m0, s38, 0x14000
	v_mov_b32_e32 v129, v193
	global_load_lds_dwordx4 v192, s[14:15]
	s_add_i32 m0, s38, 0x16000
	s_add_u32 s44, s0, s8
	s_addc_u32 s45, s1, s9
	s_add_i32 s40, s38, 0x2000
	global_load_lds_dwordx4 v128, s[14:15]
	s_mov_b32 m0, s38
	s_add_u32 s8, s44, 0x40000
	global_load_lds_dwordx4 v132, s[44:45]
	s_mov_b32 m0, s40
	s_addc_u32 s9, s45, 0
	s_add_i32 s41, s38, 0x4000
	global_load_lds_dwordx4 v130, s[44:45]
	s_mov_b32 m0, s41
	s_add_i32 s46, s38, 0x6000
	global_load_lds_dwordx4 v132, s[8:9]
	s_mov_b32 m0, s46
	v_mov_b32_e32 v133, v193
	global_load_lds_dwordx4 v130, s[8:9]
	v_mov_b32_e32 v131, v193
	s_cmp_eq_u32 s11, 1
	v_lshl_add_u64 v[6:7], s[58:59], 0, v[192:193]
	v_lshl_add_u64 v[4:5], s[58:59], 0, v[128:129]
	v_lshl_add_u64 v[0:1], s[44:45], 0, v[132:133]
	s_cselect_b64 s[8:9], -1, 0
	s_cmp_lg_u32 s11, 1
	v_lshl_add_u64 v[2:3], s[44:45], 0, v[130:131]
	s_cbranch_scc1 .LBB0_137
	s_barrier

;     __host__ __device__ bool next(int i, Unit& u) const {
;         const long L = (long)i * G + c; if (L >= nwg) return false;
;         int wgid = (int)L; { const int q = nwg / NXCD, r = nwg % NXCD, xcd = wgid % NXCD, off = wgid / NXCD; wgid = (xcd < r ? xcd * (q + 1) : r * (q + 1) + (xcd - r) * q) + off; }
;         const int nig = WGM * nN, gid = wgid / nig, fm = gid * WGM, gsz = (nM - fm) < WGM ? (nM - fm) : WGM;
;         u.pm = fm + ((wgid % nig) % gsz); u.pn = (wgid % nig) / gsz; return true;
.LBB0_140:
	s_add_i32 s54, s54, 1
	s_mul_i32 s6, s54, s53
	s_waitcnt lgkmcnt(0)
	s_mul_hi_u32 s7, s54, s75
	s_add_i32 s7, s7, s6
	s_mul_i32 s6, s54, s75
	s_add_u32 s18, s6, s68
	s_addc_u32 s19, s7, s35
	v_cmp_gt_i64_e32 vcc, s[18:19], v[250:251]
	v_cmp_lt_i64_e64 s[6:7], s[18:19], v[228:229]
	s_cbranch_vccnz .LBB0_142
	s_ashr_i32 s14, s18, 31
	s_lshr_b32 s14, s14, 29
	s_add_i32 s14, s18, s14
	s_ashr_i32 s15, s14, 3
	s_and_b32 s14, s14, -8
	s_sub_i32 s14, s18, s14
	s_cmp_lt_i32 s14, 0
	s_movk_i32 s16, 0x161
	s_cselect_b32 s16, s16, 0x160
	s_mul_i32 s14, s16, s14
	s_add_i32 s14, s14, s15
	s_mul_hi_i32 s15, s14, 0x2e8ba2e9
	s_lshr_b32 s16, s15, 31
	s_ashr_i32 s15, s15, 4
	s_add_i32 s15, s15, s16
	s_lshl_b32 s16, s15, 2
	s_sub_i32 s17, 0x80, s16
	s_min_i32 s17, s17, 4
	s_abs_i32 s18, s17
	v_cvt_f32_u32_e32 v0, s18
	s_sub_i32 s20, 0, s18
	s_mulk_i32 s15, 0x58
	s_sub_i32 s15, s14, s15
	v_rcp_iflag_f32_e32 v0, v0
	s_abs_i32 s14, s15
	s_xor_b32 s19, s15, s17
	s_ashr_i32 s19, s19, 31
	v_mul_f32_e32 v0, 0x4f7ffffe, v0
	v_cvt_u32_f32_e32 v0, v0
	s_nop 0
	v_readfirstlane_b32 s21, v0
	s_mul_i32 s20, s20, s21
	s_mul_hi_u32 s20, s21, s20
	s_add_i32 s21, s21, s20
	s_mul_hi_u32 s20, s14, s21
	s_mul_i32 s21, s20, s18
	s_sub_i32 s14, s14, s21
	s_add_i32 s55, s20, 1
	s_sub_i32 s21, s14, s18
	s_cmp_ge_u32 s14, s18
	s_cselect_b32 s20, s55, s20
	s_cselect_b32 s14, s21, s14
	s_add_i32 s21, s20, 1
	s_cmp_ge_u32 s14, s18
	s_cselect_b32 s14, s21, s20
	s_xor_b32 s14, s14, s19
	s_sub_i32 s14, s14, s19
	s_mul_i32 s17, s14, s17
	s_sub_i32 s15, s15, s17
	s_add_i32 s16, s15, s16
	s_lshr_b32 s98, s16, 3
	s_and_b32 s98, s98, 1
	s_lshl_b32 s98, s98, 6
	s_and_b32 s99, s16, 7
	s_add_i32 s98, s98, s99
	s_lshr_b32 s16, s16, 4
	s_lshl_b32 s16, s16, 3
	s_add_i32 s16, s16, s98

; __device__ __forceinline__ unsigned xb_ld(unsigned* p)              { return __hip_atomic_load(p, __ATOMIC_RELAXED, __HIP_MEMORY_SCOPE_AGENT); }
; __device__ __forceinline__ unsigned xb_add(unsigned* p, unsigned v) { return __hip_atomic_fetch_add(p, v, __ATOMIC_RELAXED, __HIP_MEMORY_SCOPE_AGENT); }
; #define XB_SPIN(cond, bar) do { unsigned _sp = 0; while (cond) { __builtin_amdgcn_s_sleep(0); \
;     if ((++_sp & 255u) == 0u) { if (xb_ld(&(bar)[XB_TMO])) break; if (_sp > XB_SPIN_CAP) { atomicAdd(&(bar)[XB_TMO], 1u); break; } } } } while (0)
; __device__ __forceinline__ void xcd_barrier(const XcdBarrier& b) {
;     ...
;         const unsigned old = xb_add(&bar[XB_XSUB(b.x)], 1u);
;         const unsigned gen = old / nloc;
;         if (old + 1u == (gen + 1u) * nloc) {
;             __builtin_amdgcn_fence(__ATOMIC_RELEASE, "agent");
;             asm volatile("s_waitcnt vmcnt(0)" ::: "memory");
;             const unsigned og = xb_add(&bar[XB_TOP], 1u);
;             const unsigned tg = og / nx;
;             if (og + 1u == (tg + 1u) * nx) xb_add(&bar[XB_TOPGEN], 1u);
;             else XB_SPIN(xb_ld(&bar[XB_TOPGEN]) == tg, bar);
;             __builtin_amdgcn_fence(__ATOMIC_ACQUIRE, "agent");
;             xb_add(&bar[XB_XGEN(b.x)], 1u);
;             asm volatile("s_waitcnt vmcnt(0)" ::: "memory");
.LBB0_756:
	s_andn2_saveexec_b64 s[10:11], s[10:11]
	s_cbranch_execz .LBB0_776
	s_mov_b64 s[10:11], exec
	v_readlane_b32 s99, v255, 42
	s_cmp_ge_u32 s3, 18
	s_cselect_b32 s98, 18, 0
	s_sub_u32 s98, s3, s98
	s_cmp_eq_u32 s99, 0
	s_cbranch_scc1 .Lfull_l
	s_cmp_eq_u32 s98, 4
	s_cbranch_scc1 .Lnf_l4
	s_cmp_eq_u32 s98, 10
	s_cbranch_scc1 .Lnf_l4
	s_cmp_eq_u32 s98, 7
	s_cbranch_scc1 .Lnf_l4
	s_cmp_eq_u32 s98, 1
	s_cbranch_scc1 .Lnf_l4
	s_cmp_eq_u32 s98, 14
	s_cbranch_scc1 .Lnf_l4
	s_cmp_eq_u32 s98, 16
	s_cbranch_scc1 .Lnf_l4
	s_cmp_eq_u32 s98, 5
	s_cbranch_scc1 .Lnf_l
	s_cmp_eq_u32 s98, 6
	s_cbranch_scc1 .Lnf_l
	s_cmp_eq_u32 s98, 11
	s_cbranch_scc1 .Lnf_l
